# scan: waves 4-7 delayed by s_sleep 8 at the start of each item's ct loop (stagger the SIMD partner waves that run the same program)
# speedup vs baseline: 1.0005x; 1.0005x over previous
; __device__ __forceinline__ unsigned pk2(float lo, float hi) { unsigned r; asm("v_cvt_pk_bf16_f32 %0, %1, %2" : "=v"(r) : "v"(lo), "v"(hi)); return r; }
; __device__ __forceinline__ float bflo(unsigned w) { return __uint_as_float(w << 16); }
; __device__ __forceinline__ float bfhi(unsigned w) { return __uint_as_float(w & 0xFFFF0000u); }
; __device__ __forceinline__ void scan_mfma(PP p, unsigned char* shm, int wv) {
;     ...
;             __syncthreads();
;             const int cq = tid & 127, tq = tid >> 7, c4 = 4 * cq;
;             const f32x4 k0 = *(const f32x4*)(p->rnn_conv_w + c4), k1 = *(const f32x4*)(p->rnn_conv_w + 512 + c4), k2 = *(const f32x4*)(p->rnn_conv_w + 1024 + c4),
;                         k3 = *(const f32x4*)(p->rnn_conv_w + 1536 + c4), kb = *(const f32x4*)(p->rnn_conv_b + c4);
;             auto ld4 = [&](int row) -> f32x4 { const u32x2 w = *(const u32x2*)(raw + row * 512 + c4); f32x4 r; r[0] = bflo(w.x); r[1] = bfhi(w.x); r[2] = bflo(w.y); r[3] = bfhi(w.y); return r; };
;             f32x4 xm2 = ld4(16 * tq), xm1 = ld4(16 * tq + 1), x0 = ld4(16 * tq + 2);
; #pragma unroll
;             for (int t = 0; t < 16; ++t) {
;                 const f32x4 xp1 = ld4(16 * tq + t + 3);
;                 const f32x4 o = kb + k0 * xm2 + k1 * xm1 + k2 * x0 + k3 * xp1;
;                 u32x2 w; w.x = pk2(o[0], o[1]); w.y = pk2(o[2], o[3]);
;                 *(u32x2*)(xs + (16 * tq + t) * XS + c4) = w;
;                 xm2 = xm1; xm1 = x0; x0 = xp1;
;             }
.LBB0_368:
	s_or_b64 exec, exec, s[30:31]
	s_waitcnt lgkmcnt(0)
	s_barrier
	s_load_dwordx4 s[36:39], s[8:9], 0x40
	v_lshlrev_b32_e32 v0, 2, v54
	v_and_b32_e32 v55, 0x1fc, v0
	v_lshlrev_b32_e32 v0, 2, v55
	s_waitcnt lgkmcnt(0)
	global_load_dwordx4 v[34:37], v0, s[36:37]
	global_load_dwordx4 v[46:49], v0, s[38:39]
	v_lshl_add_u64 v[38:39], s[36:37], 0, v[0:1]
	global_load_dwordx4 v[42:45], v0, s[36:37] offset:2048
	v_add_co_u32_e32 v38, vcc, s75, v38
	v_ashrrev_i32_e32 v56, 3, v54
	s_nop 0
	v_addc_co_u32_e32 v39, vcc, 0, v39, vcc
	global_load_dwordx4 v[50:53], v[38:39], off
	s_nop 0
	global_load_dwordx4 v[38:41], v[38:39], off offset:2048
	v_and_b32_e32 v54, -16, v56
	v_lshlrev_b32_e32 v0, 1, v55
	v_lshlrev_b32_e32 v55, 10, v54
	v_add3_u32 v57, s65, v55, v0
	ds_read2st64_b64 v[58:61], v57 offset1:2
	v_add_u32_e32 v156, s65, v0
	v_add_u32_e32 v158, v156, v55
	ds_read_b64 v[62:63], v57 offset:2048
	ds_read_b64 v[64:65], v158 offset:3072
	v_add_u32_e32 v0, 0, v0
	s_waitcnt lgkmcnt(2)
	v_lshlrev_b32_e32 v66, 16, v58
	v_and_b32_e32 v67, 0xffff0000, v58
	v_lshlrev_b32_e32 v58, 16, v59
	v_and_b32_e32 v59, 0xffff0000, v59
	v_lshlrev_b32_e32 v68, 16, v60
	v_and_b32_e32 v69, 0xffff0000, v60
	v_lshlrev_b32_e32 v60, 16, v61
	v_and_b32_e32 v61, 0xffff0000, v61
	s_waitcnt lgkmcnt(1)
	v_lshlrev_b32_e32 v70, 16, v62
	v_and_b32_e32 v71, 0xffff0000, v62
	v_lshlrev_b32_e32 v62, 16, v63
	v_and_b32_e32 v63, 0xffff0000, v63
	s_waitcnt lgkmcnt(0)
	v_lshlrev_b32_e32 v72, 16, v64
	v_and_b32_e32 v73, 0xffff0000, v64
	v_mad_u64_u32 v[54:55], s[30:31], v54, s51, v[0:1]
	v_lshlrev_b32_e32 v64, 16, v65
	v_and_b32_e32 v65, 0xffff0000, v65
	s_and_b64 s[30:31], s[22:23], exec
	s_cselect_b32 s34, s78, s5
	s_and_b32 s5, s78, 3
	s_and_b64 s[30:31], s[22:23], exec
	s_cselect_b32 s79, -1, s5
	s_ashr_i32 s5, s4, 31
	s_lshl_b64 s[4:5], s[4:5], 10
	s_mov_b32 s80, 0
	s_mov_b64 s[44:45], -1
	s_waitcnt vmcnt(3)
	v_pk_fma_f32 v[66:67], v[34:35], v[66:67], v[46:47]
	v_pk_fma_f32 v[58:59], v[36:37], v[58:59], v[48:49]
	v_pk_fma_f32 v[76:77], v[36:37], v[60:61], v[48:49]
	s_waitcnt vmcnt(2)
	v_pk_fma_f32 v[58:59], v[44:45], v[60:61], v[58:59]
	v_pk_fma_f32 v[60:61], v[42:43], v[68:69], v[66:67]
	v_pk_fma_f32 v[74:75], v[34:35], v[68:69], v[46:47]
	v_pk_fma_f32 v[78:79], v[36:37], v[62:63], v[48:49]
	s_waitcnt vmcnt(1)
	v_pk_fma_f32 v[60:61], v[50:51], v[70:71], v[60:61]
	v_pk_fma_f32 v[58:59], v[52:53], v[62:63], v[58:59]
	s_waitcnt vmcnt(0)
	v_pk_fma_f32 v[60:61], v[38:39], v[72:73], v[60:61]
	v_pk_fma_f32 v[58:59], v[40:41], v[64:65], v[58:59]
	v_cvt_pk_bf16_f32 v60, v60, v61
	v_pk_fma_f32 v[66:67], v[44:45], v[62:63], v[76:77]
	v_cvt_pk_bf16_f32 v61, v58, v59
	ds_write_b64 v54, v[60:61]
	ds_read_b64 v[58:59], v158 offset:4096
	v_pk_fma_f32 v[68:69], v[42:43], v[70:71], v[74:75]
	v_pk_fma_f32 v[146:147], v[36:37], v[64:65], v[48:49]
	v_pk_fma_f32 v[62:63], v[44:45], v[64:65], v[78:79]
	v_pk_fma_f32 v[68:69], v[50:51], v[72:73], v[68:69]
	v_pk_fma_f32 v[64:65], v[52:53], v[64:65], v[66:67]
	s_waitcnt lgkmcnt(0)
	v_lshlrev_b32_e32 v66, 16, v58
	v_and_b32_e32 v67, 0xffff0000, v58
	v_lshlrev_b32_e32 v58, 16, v59
	v_and_b32_e32 v59, 0xffff0000, v59
	v_pk_fma_f32 v[68:69], v[38:39], v[66:67], v[68:69]
	v_pk_fma_f32 v[64:65], v[40:41], v[58:59], v[64:65]
	v_cvt_pk_bf16_f32 v68, v68, v69
	v_pk_fma_f32 v[80:81], v[34:35], v[70:71], v[46:47]
	v_cvt_pk_bf16_f32 v69, v64, v65
	ds_write_b64 v54, v[68:69] offset:1040
	ds_read_b64 v[64:65], v158 offset:5120
	v_pk_fma_f32 v[60:61], v[42:43], v[72:73], v[80:81]
	v_pk_fma_f32 v[154:155], v[34:35], v[72:73], v[46:47]
	v_pk_fma_f32 v[60:61], v[50:51], v[66:67], v[60:61]
	v_pk_fma_f32 v[62:63], v[52:53], v[58:59], v[62:63]
	s_waitcnt lgkmcnt(0)
	v_lshlrev_b32_e32 v72, 16, v64
	v_and_b32_e32 v73, 0xffff0000, v64
	v_lshlrev_b32_e32 v64, 16, v65
	v_and_b32_e32 v65, 0xffff0000, v65
	v_pk_fma_f32 v[60:61], v[38:39], v[72:73], v[60:61]
	v_pk_fma_f32 v[62:63], v[40:41], v[64:65], v[62:63]
	v_cvt_pk_bf16_f32 v60, v60, v61
	v_pk_fma_f32 v[68:69], v[44:45], v[58:59], v[146:147]
	v_cvt_pk_bf16_f32 v61, v62, v63
	ds_write_b64 v54, v[60:61] offset:2080
	ds_read_b64 v[60:61], v158 offset:6144
	v_pk_fma_f32 v[70:71], v[42:43], v[66:67], v[154:155]
	v_pk_fma_f32 v[62:63], v[52:53], v[64:65], v[68:69]
	v_pk_fma_f32 v[68:69], v[50:51], v[72:73], v[70:71]
	v_pk_fma_f32 v[66:67], v[34:35], v[66:67], v[46:47]
	s_waitcnt lgkmcnt(0)
	v_lshlrev_b32_e32 v70, 16, v60
	v_and_b32_e32 v71, 0xffff0000, v60
	v_lshlrev_b32_e32 v60, 16, v61
	v_and_b32_e32 v61, 0xffff0000, v61
	v_pk_fma_f32 v[68:69], v[38:39], v[70:71], v[68:69]
	v_pk_fma_f32 v[62:63], v[40:41], v[60:61], v[62:63]
	v_cvt_pk_bf16_f32 v68, v68, v69
	v_pk_fma_f32 v[58:59], v[36:37], v[58:59], v[48:49]
	v_cvt_pk_bf16_f32 v69, v62, v63
	ds_write_b64 v54, v[68:69] offset:3120
	ds_read_b64 v[62:63], v158 offset:7168
	v_pk_fma_f32 v[66:67], v[42:43], v[72:73], v[66:67]
	v_pk_fma_f32 v[58:59], v[44:45], v[64:65], v[58:59]
	v_pk_fma_f32 v[68:69], v[34:35], v[72:73], v[46:47]
	v_pk_fma_f32 v[66:67], v[50:51], v[70:71], v[66:67]
	s_waitcnt lgkmcnt(0)
	v_lshlrev_b32_e32 v72, 16, v62
	v_and_b32_e32 v73, 0xffff0000, v62
	v_pk_fma_f32 v[58:59], v[52:53], v[60:61], v[58:59]
	v_lshlrev_b32_e32 v62, 16, v63
	v_and_b32_e32 v63, 0xffff0000, v63
	v_pk_fma_f32 v[66:67], v[38:39], v[72:73], v[66:67]
	v_pk_fma_f32 v[58:59], v[40:41], v[62:63], v[58:59]
	v_cvt_pk_bf16_f32 v66, v66, v67
	v_pk_fma_f32 v[64:65], v[36:37], v[64:65], v[48:49]
	v_cvt_pk_bf16_f32 v67, v58, v59
	ds_write_b64 v54, v[66:67] offset:4160
	ds_read_b64 v[58:59], v158 offset:8192
	v_pk_fma_f32 v[66:67], v[42:43], v[70:71], v[68:69]
	v_pk_fma_f32 v[64:65], v[44:45], v[60:61], v[64:65]
	v_pk_fma_f32 v[66:67], v[50:51], v[72:73], v[66:67]
	v_pk_fma_f32 v[64:65], v[52:53], v[62:63], v[64:65]
	s_waitcnt lgkmcnt(0)
; __device__ __forceinline__ unsigned pk2(float lo, float hi) { unsigned r; asm("v_cvt_pk_bf16_f32 %0, %1, %2" : "=v"(r) : "v"(lo), "v"(hi)); return r; }
; __device__ __forceinline__ void scan_mfma(PP p, unsigned char* shm, int wv) {
;     ...
; #pragma unroll
;             for (int t = 0; t < 16; ++t) {
;                 const f32x4 xp1 = ld4(16 * tq + t + 3);
;                 const f32x4 o = kb + k0 * xm2 + k1 * xm1 + k2 * x0 + k3 * xp1;
;                 u32x2 w; w.x = pk2(o[0], o[1]); w.y = pk2(o[2], o[3]);
;                 *(u32x2*)(xs + (16 * tq + t) * XS + c4) = w;
;                 xm2 = xm1; xm1 = x0; x0 = xp1;
;             }
	v_lshlrev_b32_e32 v68, 16, v58
	v_and_b32_e32 v69, 0xffff0000, v58
	v_lshlrev_b32_e32 v58, 16, v59
	v_and_b32_e32 v59, 0xffff0000, v59
	v_pk_fma_f32 v[66:67], v[38:39], v[68:69], v[66:67]
	v_pk_fma_f32 v[64:65], v[40:41], v[58:59], v[64:65]
	v_cvt_pk_bf16_f32 v66, v66, v67
	v_pk_fma_f32 v[70:71], v[34:35], v[70:71], v[46:47]
	v_cvt_pk_bf16_f32 v67, v64, v65
	ds_write_b64 v54, v[66:67] offset:5200
	ds_read_b64 v[64:65], v158 offset:9216
	v_pk_fma_f32 v[60:61], v[36:37], v[60:61], v[48:49]
	v_pk_fma_f32 v[70:71], v[42:43], v[72:73], v[70:71]
	v_pk_fma_f32 v[60:61], v[44:45], v[62:63], v[60:61]
	v_pk_fma_f32 v[70:71], v[50:51], v[68:69], v[70:71]
	s_waitcnt lgkmcnt(0)
	v_lshlrev_b32_e32 v66, 16, v64
	v_and_b32_e32 v67, 0xffff0000, v64
	v_lshlrev_b32_e32 v64, 16, v65
	v_and_b32_e32 v65, 0xffff0000, v65
	v_pk_fma_f32 v[60:61], v[52:53], v[58:59], v[60:61]
	v_pk_fma_f32 v[70:71], v[38:39], v[66:67], v[70:71]
	v_pk_fma_f32 v[60:61], v[40:41], v[64:65], v[60:61]
	v_cvt_pk_bf16_f32 v70, v70, v71
	v_pk_fma_f32 v[72:73], v[34:35], v[72:73], v[46:47]
	v_cvt_pk_bf16_f32 v71, v60, v61
	ds_write_b64 v54, v[70:71] offset:6240
	ds_read_b64 v[60:61], v158 offset:10240
	v_pk_fma_f32 v[62:63], v[36:37], v[62:63], v[48:49]
	v_pk_fma_f32 v[72:73], v[42:43], v[68:69], v[72:73]
	v_pk_fma_f32 v[62:63], v[44:45], v[58:59], v[62:63]
	v_pk_fma_f32 v[72:73], v[50:51], v[66:67], v[72:73]
	s_waitcnt lgkmcnt(0)
	v_lshlrev_b32_e32 v70, 16, v60
	v_and_b32_e32 v71, 0xffff0000, v60
	v_lshlrev_b32_e32 v60, 16, v61
	v_and_b32_e32 v61, 0xffff0000, v61
	v_pk_fma_f32 v[62:63], v[52:53], v[64:65], v[62:63]
	v_pk_fma_f32 v[72:73], v[38:39], v[70:71], v[72:73]
	v_pk_fma_f32 v[62:63], v[40:41], v[60:61], v[62:63]
	v_cvt_pk_bf16_f32 v72, v72, v73
	v_pk_fma_f32 v[68:69], v[34:35], v[68:69], v[46:47]
	v_cvt_pk_bf16_f32 v73, v62, v63
	ds_write_b64 v54, v[72:73] offset:7280
	ds_read_b64 v[62:63], v158 offset:11264
	v_pk_fma_f32 v[58:59], v[36:37], v[58:59], v[48:49]
	v_pk_fma_f32 v[68:69], v[42:43], v[66:67], v[68:69]
	v_pk_fma_f32 v[58:59], v[44:45], v[64:65], v[58:59]
	v_pk_fma_f32 v[68:69], v[50:51], v[70:71], v[68:69]
	s_waitcnt lgkmcnt(0)
	v_lshlrev_b32_e32 v72, 16, v62
	v_and_b32_e32 v73, 0xffff0000, v62
	v_lshlrev_b32_e32 v62, 16, v63
	v_and_b32_e32 v63, 0xffff0000, v63
	v_pk_fma_f32 v[58:59], v[52:53], v[60:61], v[58:59]
	v_pk_fma_f32 v[68:69], v[38:39], v[72:73], v[68:69]
	v_pk_fma_f32 v[58:59], v[40:41], v[62:63], v[58:59]
	v_cvt_pk_bf16_f32 v68, v68, v69
	v_pk_fma_f32 v[66:67], v[34:35], v[66:67], v[46:47]
	v_cvt_pk_bf16_f32 v69, v58, v59
	ds_write_b64 v54, v[68:69] offset:8320
	ds_read_b64 v[58:59], v158 offset:12288
	v_pk_fma_f32 v[64:65], v[36:37], v[64:65], v[48:49]
	v_pk_fma_f32 v[66:67], v[42:43], v[70:71], v[66:67]
	v_pk_fma_f32 v[64:65], v[44:45], v[60:61], v[64:65]
	v_pk_fma_f32 v[66:67], v[50:51], v[72:73], v[66:67]
	s_waitcnt lgkmcnt(0)
	v_lshlrev_b32_e32 v68, 16, v58
	v_and_b32_e32 v69, 0xffff0000, v58
	v_lshlrev_b32_e32 v58, 16, v59
	v_and_b32_e32 v59, 0xffff0000, v59
	v_pk_fma_f32 v[64:65], v[52:53], v[62:63], v[64:65]
	v_pk_fma_f32 v[66:67], v[38:39], v[68:69], v[66:67]
	v_pk_fma_f32 v[64:65], v[40:41], v[58:59], v[64:65]
	v_cvt_pk_bf16_f32 v66, v66, v67
	v_pk_fma_f32 v[70:71], v[34:35], v[70:71], v[46:47]
	v_cvt_pk_bf16_f32 v67, v64, v65
	ds_write_b64 v54, v[66:67] offset:9360
	ds_read_b64 v[64:65], v158 offset:13312
	v_pk_fma_f32 v[60:61], v[36:37], v[60:61], v[48:49]
	v_pk_fma_f32 v[70:71], v[42:43], v[72:73], v[70:71]
	v_pk_fma_f32 v[60:61], v[44:45], v[62:63], v[60:61]
	v_pk_fma_f32 v[70:71], v[50:51], v[68:69], v[70:71]
	s_waitcnt lgkmcnt(0)
	v_lshlrev_b32_e32 v66, 16, v64
	v_and_b32_e32 v67, 0xffff0000, v64
	v_lshlrev_b32_e32 v64, 16, v65
	v_and_b32_e32 v65, 0xffff0000, v65
	v_pk_fma_f32 v[60:61], v[52:53], v[58:59], v[60:61]
	v_pk_fma_f32 v[70:71], v[38:39], v[66:67], v[70:71]
	v_pk_fma_f32 v[60:61], v[40:41], v[64:65], v[60:61]
	v_cvt_pk_bf16_f32 v70, v70, v71
	v_pk_fma_f32 v[72:73], v[34:35], v[72:73], v[46:47]
	v_cvt_pk_bf16_f32 v71, v60, v61
	ds_write_b64 v54, v[70:71] offset:10400
	ds_read_b64 v[60:61], v158 offset:14336
	v_pk_fma_f32 v[62:63], v[36:37], v[62:63], v[48:49]
	v_pk_fma_f32 v[72:73], v[42:43], v[68:69], v[72:73]
	v_pk_fma_f32 v[62:63], v[44:45], v[58:59], v[62:63]
	v_pk_fma_f32 v[72:73], v[50:51], v[66:67], v[72:73]
	s_waitcnt lgkmcnt(0)
; __device__ __forceinline__ unsigned pk2(float lo, float hi) { unsigned r; asm("v_cvt_pk_bf16_f32 %0, %1, %2" : "=v"(r) : "v"(lo), "v"(hi)); return r; }
; __device__ __forceinline__ void scan_mfma(PP p, unsigned char* shm, int wv) {
;     ...
; #pragma unroll
;             for (int t = 0; t < 16; ++t) {
;                 const f32x4 xp1 = ld4(16 * tq + t + 3);
;                 const f32x4 o = kb + k0 * xm2 + k1 * xm1 + k2 * x0 + k3 * xp1;
;                 u32x2 w; w.x = pk2(o[0], o[1]); w.y = pk2(o[2], o[3]);
;                 *(u32x2*)(xs + (16 * tq + t) * XS + c4) = w;
;                 xm2 = xm1; xm1 = x0; x0 = xp1;
;             }
;         }
;         __syncthreads();
; #pragma unroll 1
;         for (int ct = 0; ct < 2; ++ct) {
	v_lshlrev_b32_e32 v70, 16, v60
	v_and_b32_e32 v71, 0xffff0000, v60
	v_lshlrev_b32_e32 v60, 16, v61
	v_and_b32_e32 v61, 0xffff0000, v61
	v_pk_fma_f32 v[62:63], v[52:53], v[64:65], v[62:63]
	v_pk_fma_f32 v[72:73], v[38:39], v[70:71], v[72:73]
	v_pk_fma_f32 v[62:63], v[40:41], v[60:61], v[62:63]
	v_cvt_pk_bf16_f32 v72, v72, v73
	v_pk_fma_f32 v[68:69], v[34:35], v[68:69], v[46:47]
	v_cvt_pk_bf16_f32 v73, v62, v63
	ds_write_b64 v54, v[72:73] offset:11440
	ds_read_b64 v[62:63], v158 offset:15360
	v_pk_fma_f32 v[58:59], v[36:37], v[58:59], v[48:49]
	v_pk_fma_f32 v[68:69], v[42:43], v[66:67], v[68:69]
	v_pk_fma_f32 v[58:59], v[44:45], v[64:65], v[58:59]
	v_pk_fma_f32 v[68:69], v[50:51], v[70:71], v[68:69]
	s_waitcnt lgkmcnt(0)
	v_lshlrev_b32_e32 v72, 16, v62
	v_and_b32_e32 v73, 0xffff0000, v62
	v_lshlrev_b32_e32 v62, 16, v63
	v_and_b32_e32 v63, 0xffff0000, v63
	v_pk_fma_f32 v[58:59], v[52:53], v[60:61], v[58:59]
	v_pk_fma_f32 v[68:69], v[38:39], v[72:73], v[68:69]
	v_pk_fma_f32 v[58:59], v[40:41], v[62:63], v[58:59]
	v_cvt_pk_bf16_f32 v68, v68, v69
	v_pk_fma_f32 v[66:67], v[34:35], v[66:67], v[46:47]
	v_cvt_pk_bf16_f32 v69, v58, v59
	ds_write_b64 v54, v[68:69] offset:12480
	ds_read_b64 v[58:59], v158 offset:16384
	v_pk_fma_f32 v[64:65], v[36:37], v[64:65], v[48:49]
	v_pk_fma_f32 v[66:67], v[42:43], v[70:71], v[66:67]
	v_pk_fma_f32 v[64:65], v[44:45], v[60:61], v[64:65]
	v_pk_fma_f32 v[66:67], v[50:51], v[72:73], v[66:67]
	s_waitcnt lgkmcnt(0)
	v_lshlrev_b32_e32 v68, 16, v58
	v_and_b32_e32 v69, 0xffff0000, v58
	v_lshlrev_b32_e32 v58, 16, v59
	v_and_b32_e32 v59, 0xffff0000, v59
	v_pk_fma_f32 v[64:65], v[52:53], v[62:63], v[64:65]
	v_pk_fma_f32 v[66:67], v[38:39], v[68:69], v[66:67]
	v_pk_fma_f32 v[64:65], v[40:41], v[58:59], v[64:65]
	v_cvt_pk_bf16_f32 v66, v66, v67
	v_pk_fma_f32 v[60:61], v[36:37], v[60:61], v[48:49]
	v_cvt_pk_bf16_f32 v67, v64, v65
	ds_write_b64 v54, v[66:67] offset:13520
	ds_read_b64 v[64:65], v158 offset:17408
	v_pk_fma_f32 v[70:71], v[34:35], v[70:71], v[46:47]
	v_pk_fma_f32 v[60:61], v[44:45], v[62:63], v[60:61]
	v_pk_fma_f32 v[70:71], v[42:43], v[72:73], v[70:71]
	v_pk_fma_f32 v[60:61], v[52:53], v[58:59], v[60:61]
	s_waitcnt lgkmcnt(0)
	v_lshlrev_b32_e32 v66, 16, v64
	v_and_b32_e32 v67, 0xffff0000, v64
	v_lshlrev_b32_e32 v64, 16, v65
	v_and_b32_e32 v65, 0xffff0000, v65
	v_pk_fma_f32 v[70:71], v[50:51], v[68:69], v[70:71]
	v_pk_fma_f32 v[60:61], v[40:41], v[64:65], v[60:61]
	v_pk_fma_f32 v[70:71], v[38:39], v[66:67], v[70:71]
	v_pk_fma_f32 v[36:37], v[36:37], v[62:63], v[48:49]
	v_cvt_pk_bf16_f32 v70, v70, v71
	v_cvt_pk_bf16_f32 v71, v60, v61
	v_or_b32_e32 v60, 15, v56
	ds_write_b64 v54, v[70:71] offset:14560
	v_lshl_add_u32 v54, v60, 10, v156
	ds_read_b64 v[54:55], v54 offset:3072
	v_pk_fma_f32 v[34:35], v[34:35], v[72:73], v[46:47]
	v_pk_fma_f32 v[36:37], v[44:45], v[58:59], v[36:37]
	v_pk_fma_f32 v[34:35], v[42:43], v[68:69], v[34:35]
	v_pk_fma_f32 v[36:37], v[52:53], v[64:65], v[36:37]
	s_waitcnt lgkmcnt(0)
	v_lshlrev_b32_e32 v56, 16, v54
	v_and_b32_e32 v57, 0xffff0000, v54
	v_lshlrev_b32_e32 v54, 16, v55
	v_and_b32_e32 v55, 0xffff0000, v55
	v_pk_fma_f32 v[34:35], v[50:51], v[66:67], v[34:35]
	v_pk_fma_f32 v[36:37], v[40:41], v[54:55], v[36:37]
	v_pk_fma_f32 v[34:35], v[38:39], v[56:57], v[34:35]
	s_nop 0
	v_cvt_pk_bf16_f32 v34, v34, v35
	v_cvt_pk_bf16_f32 v35, v36, v37
	v_mad_u64_u32 v[36:37], s[30:31], v60, s51, v[0:1]
	s_add_u32 s30, s52, s4
	s_addc_u32 s31, s53, s5
	s_ashr_i32 s35, s34, 31
	s_lshl_b64 s[34:35], s[34:35], 12
	s_add_u32 s34, s54, s34
	s_addc_u32 s35, s55, s35
	s_add_u32 s36, s57, s4
	s_addc_u32 s37, s58, s5
	s_add_u32 s38, s59, s4
	s_addc_u32 s39, s60, s5
	s_add_u32 s40, s34, 0x208000
	s_addc_u32 s41, s35, 0
	ds_write_b64 v36, v[34:35]
	s_waitcnt lgkmcnt(0)
	s_barrier
	s_cmpk_lt_u32 s33, 0x100
	s_cbranch_scc1 .Lscan_nostagger
	s_sleep 8
.Lscan_nostagger:
	s_branch .LBB0_371
